# local seams invalidate only the CU vector L1 (buffer_inv sc0) instead of agent scope: no cross-XCD data flows after the first barrier in co-located mode, so the XCD L2 keeps its contents across seams
# speedup vs baseline: 1.0151x; 1.0151x over previous
; __device__ __forceinline__ unsigned xb_ld(unsigned* p)              { return __hip_atomic_load(p, __ATOMIC_RELAXED, __HIP_MEMORY_SCOPE_AGENT); }
; #define XB_SPIN(cond, bar) do { unsigned _sp = 0; while (cond) { __builtin_amdgcn_s_sleep(1); \
;     if ((++_sp & 255u) == 0u) { if (xb_ld(&(bar)[XB_TMO])) break; if (_sp > XB_SPIN_CAP) { atomicAdd(&(bar)[XB_TMO], 1u); break; } } } } while (0)
; __device__ __forceinline__ void xcd_barrier(const XcdBarrier& b) {
;     ...
;             XB_SPIN(xb_ld(&bar[XB_XGEN(b.x)]) == gen, bar);
;             __builtin_amdgcn_fence(__ATOMIC_ACQUIRE, "agent");
;             asm volatile("s_waitcnt vmcnt(0)" ::: "memory");
.Lfb_done_2:
	buffer_inv sc0
	s_waitcnt vmcnt(0)
	s_branch .LBB0_687
